# LN1 phase router-logit MFMA stage: weight fragments read from LDS a whole k-step (6 fragments) ahead instead of read->wait->mfma one by one; MFMAs of one accumulator spaced
# speedup vs baseline: 1.0036x; 1.0036x over previous
; #define LAS __attribute__((address_space(3)))
; __device__ __forceinline__ void ln1_router_phase(CArgs& A, Frame& F, int L) {
;     ...
; #pragma unroll 1
;         for (int half = 0; half < 2; ++half) {
;             bf16x8 af[16];
; #pragma unroll
;             for (int ks = 0; ks < 16; ++ks) af[ks] = *(const bf16x8*)(xr + 32 * (16 * half + ks));
; #pragma unroll
;             for (int ks = 0; ks < 16; ++ks)
; #pragma unroll
;                 for (int nt = 0; nt < 3; ++nt) { const int off = orow[nt] + 32 * (16 * half + ks);
;                     const bf16x8 bh = *(const LAS bf16x8*)(Wh + off), bl = *(const LAS bf16x8*)(Wl + off);
;                     lacc[nt] = __builtin_amdgcn_mfma_f32_16x16x32_bf16(bh, af[ks], lacc[nt], 0, 0, 0);
;                     lacc[nt] = __builtin_amdgcn_mfma_f32_16x16x32_bf16(bl, af[ks], lacc[nt], 0, 0, 0); } }
.LBB0_1171:
	v_cndmask_b32_e64 v4, 0, 1, s[6:7]
	v_cmp_ne_u32_e32 vcc, 1, v4
	v_lshl_add_u64 v[4:5], s[8:9], 1, v[80:81]
	global_load_dwordx4 v[92:95], v[4:5], off
	global_load_dwordx4 v[72:75], v[4:5], off offset:64
	global_load_dwordx4 v[64:67], v[4:5], off offset:128
	global_load_dwordx4 v[60:63], v[4:5], off offset:192
	global_load_dwordx4 v[56:59], v[4:5], off offset:256
	global_load_dwordx4 v[52:55], v[4:5], off offset:320
	global_load_dwordx4 v[48:51], v[4:5], off offset:384
	global_load_dwordx4 v[44:47], v[4:5], off offset:448
	global_load_dwordx4 v[40:43], v[4:5], off offset:512
	global_load_dwordx4 v[36:39], v[4:5], off offset:576
	global_load_dwordx4 v[32:35], v[4:5], off offset:640
	global_load_dwordx4 v[28:31], v[4:5], off offset:704
	global_load_dwordx4 v[24:27], v[4:5], off offset:768
	global_load_dwordx4 v[20:23], v[4:5], off offset:832
	global_load_dwordx4 v[8:11], v[4:5], off offset:896
	s_nop 0
	global_load_dwordx4 v[4:7], v[4:5], off offset:960
	v_add_lshl_u32 v152, s8, v83, 1
	v_add_lshl_u32 v153, s8, v84, 1
	v_add_lshl_u32 v154, s8, v85, 1
	v_add_u32_e32 v155, s63, v152
	v_add_u32_e32 v156, s63, v153
	v_add_u32_e32 v157, s63, v154
	s_movk_i32 s8, 0x200
	s_and_b64 vcc, exec, vcc
	ds_read_b128 v[104:107], v152 offset:0
	ds_read_b128 v[108:111], v155 offset:0
	ds_read_b128 v[112:115], v153 offset:0
	ds_read_b128 v[116:119], v156 offset:0
	ds_read_b128 v[120:123], v154 offset:0
	ds_read_b128 v[124:127], v157 offset:0
	ds_read_b128 v[128:131], v152 offset:64
	ds_read_b128 v[132:135], v155 offset:64
	ds_read_b128 v[136:139], v153 offset:64
	ds_read_b128 v[140:143], v156 offset:64
	ds_read_b128 v[144:147], v154 offset:64
	ds_read_b128 v[148:151], v157 offset:64
	s_waitcnt vmcnt(15) lgkmcnt(6)
	v_mfma_f32_16x16x32_bf16 v[16:19], v[104:107], v[92:95], v[16:19]
	v_mfma_f32_16x16x32_bf16 v[12:15], v[112:115], v[92:95], v[12:15]
	v_mfma_f32_16x16x32_bf16 v[68:71], v[120:123], v[92:95], v[68:71]
	v_mfma_f32_16x16x32_bf16 v[16:19], v[108:111], v[92:95], v[16:19]
	v_mfma_f32_16x16x32_bf16 v[12:15], v[116:119], v[92:95], v[12:15]
	v_mfma_f32_16x16x32_bf16 v[68:71], v[124:127], v[92:95], v[68:71]
	ds_read_b128 v[104:107], v152 offset:128
	ds_read_b128 v[108:111], v155 offset:128
	ds_read_b128 v[112:115], v153 offset:128
	ds_read_b128 v[116:119], v156 offset:128
	ds_read_b128 v[120:123], v154 offset:128
	ds_read_b128 v[124:127], v157 offset:128
	s_waitcnt vmcnt(14) lgkmcnt(6)
	v_mfma_f32_16x16x32_bf16 v[16:19], v[128:131], v[72:75], v[16:19]
	v_mfma_f32_16x16x32_bf16 v[12:15], v[136:139], v[72:75], v[12:15]
	v_mfma_f32_16x16x32_bf16 v[68:71], v[144:147], v[72:75], v[68:71]
	v_mfma_f32_16x16x32_bf16 v[16:19], v[132:135], v[72:75], v[16:19]
	v_mfma_f32_16x16x32_bf16 v[12:15], v[140:143], v[72:75], v[12:15]
	v_mfma_f32_16x16x32_bf16 v[68:71], v[148:151], v[72:75], v[68:71]
	ds_read_b128 v[128:131], v152 offset:192
	ds_read_b128 v[132:135], v155 offset:192
	ds_read_b128 v[136:139], v153 offset:192
	ds_read_b128 v[140:143], v156 offset:192
	ds_read_b128 v[144:147], v154 offset:192
	ds_read_b128 v[148:151], v157 offset:192
	s_waitcnt vmcnt(13) lgkmcnt(6)
	v_mfma_f32_16x16x32_bf16 v[16:19], v[104:107], v[64:67], v[16:19]
	v_mfma_f32_16x16x32_bf16 v[12:15], v[112:115], v[64:67], v[12:15]
	v_mfma_f32_16x16x32_bf16 v[68:71], v[120:123], v[64:67], v[68:71]
	v_mfma_f32_16x16x32_bf16 v[16:19], v[108:111], v[64:67], v[16:19]
	v_mfma_f32_16x16x32_bf16 v[12:15], v[116:119], v[64:67], v[12:15]
	v_mfma_f32_16x16x32_bf16 v[68:71], v[124:127], v[64:67], v[68:71]
	ds_read_b128 v[104:107], v152 offset:256
	ds_read_b128 v[108:111], v155 offset:256
	ds_read_b128 v[112:115], v153 offset:256
	ds_read_b128 v[116:119], v156 offset:256
	ds_read_b128 v[120:123], v154 offset:256
	ds_read_b128 v[124:127], v157 offset:256
	s_waitcnt vmcnt(12) lgkmcnt(6)
	v_mfma_f32_16x16x32_bf16 v[16:19], v[128:131], v[60:63], v[16:19]
	v_mfma_f32_16x16x32_bf16 v[12:15], v[136:139], v[60:63], v[12:15]
	v_mfma_f32_16x16x32_bf16 v[68:71], v[144:147], v[60:63], v[68:71]
	v_mfma_f32_16x16x32_bf16 v[16:19], v[132:135], v[60:63], v[16:19]
	v_mfma_f32_16x16x32_bf16 v[12:15], v[140:143], v[60:63], v[12:15]
	v_mfma_f32_16x16x32_bf16 v[68:71], v[148:151], v[60:63], v[68:71]
	ds_read_b128 v[128:131], v152 offset:320
	ds_read_b128 v[132:135], v155 offset:320
	ds_read_b128 v[136:139], v153 offset:320
	ds_read_b128 v[140:143], v156 offset:320
	ds_read_b128 v[144:147], v154 offset:320
	ds_read_b128 v[148:151], v157 offset:320
	s_waitcnt vmcnt(11) lgkmcnt(6)
	v_mfma_f32_16x16x32_bf16 v[16:19], v[104:107], v[56:59], v[16:19]
	v_mfma_f32_16x16x32_bf16 v[12:15], v[112:115], v[56:59], v[12:15]
	v_mfma_f32_16x16x32_bf16 v[68:71], v[120:123], v[56:59], v[68:71]
	v_mfma_f32_16x16x32_bf16 v[16:19], v[108:111], v[56:59], v[16:19]
	v_mfma_f32_16x16x32_bf16 v[12:15], v[116:119], v[56:59], v[12:15]
	v_mfma_f32_16x16x32_bf16 v[68:71], v[124:127], v[56:59], v[68:71]
	ds_read_b128 v[104:107], v152 offset:384
	ds_read_b128 v[108:111], v155 offset:384
	ds_read_b128 v[112:115], v153 offset:384
	ds_read_b128 v[116:119], v156 offset:384
	ds_read_b128 v[120:123], v154 offset:384
	ds_read_b128 v[124:127], v157 offset:384
	s_waitcnt vmcnt(10) lgkmcnt(6)
	v_mfma_f32_16x16x32_bf16 v[16:19], v[128:131], v[52:55], v[16:19]
	v_mfma_f32_16x16x32_bf16 v[12:15], v[136:139], v[52:55], v[12:15]
	v_mfma_f32_16x16x32_bf16 v[68:71], v[144:147], v[52:55], v[68:71]
	v_mfma_f32_16x16x32_bf16 v[16:19], v[132:135], v[52:55], v[16:19]
	v_mfma_f32_16x16x32_bf16 v[12:15], v[140:143], v[52:55], v[12:15]
	v_mfma_f32_16x16x32_bf16 v[68:71], v[148:151], v[52:55], v[68:71]
	ds_read_b128 v[128:131], v152 offset:448
	ds_read_b128 v[132:135], v155 offset:448
	ds_read_b128 v[136:139], v153 offset:448
	ds_read_b128 v[140:143], v156 offset:448
	ds_read_b128 v[144:147], v154 offset:448
	ds_read_b128 v[148:151], v157 offset:448
	s_waitcnt vmcnt(9) lgkmcnt(6)
; #define LAS __attribute__((address_space(3)))
; __device__ __forceinline__ void ln1_router_phase(CArgs& A, Frame& F, int L) {
;     ...
; #pragma unroll
;             for (int ks = 0; ks < 16; ++ks) af[ks] = *(const bf16x8*)(xr + 32 * (16 * half + ks));
; #pragma unroll
;             for (int ks = 0; ks < 16; ++ks)
; #pragma unroll
;                 for (int nt = 0; nt < 3; ++nt) { const int off = orow[nt] + 32 * (16 * half + ks);
;                     const bf16x8 bh = *(const LAS bf16x8*)(Wh + off), bl = *(const LAS bf16x8*)(Wl + off);
;                     lacc[nt] = __builtin_amdgcn_mfma_f32_16x16x32_bf16(bh, af[ks], lacc[nt], 0, 0, 0);
;                     lacc[nt] = __builtin_amdgcn_mfma_f32_16x16x32_bf16(bl, af[ks], lacc[nt], 0, 0, 0); } }
;         if (r0 + 16 * tile + fr < r1) {
; #pragma unroll
;             for (int nt = 0; nt < 3; ++nt) *(f32x4*)(LG + (size_t)trow * 48 + 16 * nt + 4 * fq) = lacc[nt]; }
	v_mfma_f32_16x16x32_bf16 v[16:19], v[104:107], v[48:51], v[16:19]
	v_mfma_f32_16x16x32_bf16 v[12:15], v[112:115], v[48:51], v[12:15]
	v_mfma_f32_16x16x32_bf16 v[68:71], v[120:123], v[48:51], v[68:71]
	v_mfma_f32_16x16x32_bf16 v[16:19], v[108:111], v[48:51], v[16:19]
	v_mfma_f32_16x16x32_bf16 v[12:15], v[116:119], v[48:51], v[12:15]
	v_mfma_f32_16x16x32_bf16 v[68:71], v[124:127], v[48:51], v[68:71]
	ds_read_b128 v[104:107], v152 offset:512
	ds_read_b128 v[108:111], v155 offset:512
	ds_read_b128 v[112:115], v153 offset:512
	ds_read_b128 v[116:119], v156 offset:512
	ds_read_b128 v[120:123], v154 offset:512
	ds_read_b128 v[124:127], v157 offset:512
	s_waitcnt vmcnt(8) lgkmcnt(6)
	v_mfma_f32_16x16x32_bf16 v[16:19], v[128:131], v[44:47], v[16:19]
	v_mfma_f32_16x16x32_bf16 v[12:15], v[136:139], v[44:47], v[12:15]
	v_mfma_f32_16x16x32_bf16 v[68:71], v[144:147], v[44:47], v[68:71]
	v_mfma_f32_16x16x32_bf16 v[16:19], v[132:135], v[44:47], v[16:19]
	v_mfma_f32_16x16x32_bf16 v[12:15], v[140:143], v[44:47], v[12:15]
	v_mfma_f32_16x16x32_bf16 v[68:71], v[148:151], v[44:47], v[68:71]
	ds_read_b128 v[128:131], v152 offset:576
	ds_read_b128 v[132:135], v155 offset:576
	ds_read_b128 v[136:139], v153 offset:576
	ds_read_b128 v[140:143], v156 offset:576
	ds_read_b128 v[144:147], v154 offset:576
	ds_read_b128 v[148:151], v157 offset:576
	s_waitcnt vmcnt(7) lgkmcnt(6)
	v_mfma_f32_16x16x32_bf16 v[16:19], v[104:107], v[40:43], v[16:19]
	v_mfma_f32_16x16x32_bf16 v[12:15], v[112:115], v[40:43], v[12:15]
	v_mfma_f32_16x16x32_bf16 v[68:71], v[120:123], v[40:43], v[68:71]
	v_mfma_f32_16x16x32_bf16 v[16:19], v[108:111], v[40:43], v[16:19]
	v_mfma_f32_16x16x32_bf16 v[12:15], v[116:119], v[40:43], v[12:15]
	v_mfma_f32_16x16x32_bf16 v[68:71], v[124:127], v[40:43], v[68:71]
	ds_read_b128 v[104:107], v152 offset:640
	ds_read_b128 v[108:111], v155 offset:640
	ds_read_b128 v[112:115], v153 offset:640
	ds_read_b128 v[116:119], v156 offset:640
	ds_read_b128 v[120:123], v154 offset:640
	ds_read_b128 v[124:127], v157 offset:640
	s_waitcnt vmcnt(6) lgkmcnt(6)
	v_mfma_f32_16x16x32_bf16 v[16:19], v[128:131], v[36:39], v[16:19]
	v_mfma_f32_16x16x32_bf16 v[12:15], v[136:139], v[36:39], v[12:15]
	v_mfma_f32_16x16x32_bf16 v[68:71], v[144:147], v[36:39], v[68:71]
	v_mfma_f32_16x16x32_bf16 v[16:19], v[132:135], v[36:39], v[16:19]
	v_mfma_f32_16x16x32_bf16 v[12:15], v[140:143], v[36:39], v[12:15]
	v_mfma_f32_16x16x32_bf16 v[68:71], v[148:151], v[36:39], v[68:71]
	ds_read_b128 v[128:131], v152 offset:704
	ds_read_b128 v[132:135], v155 offset:704
	ds_read_b128 v[136:139], v153 offset:704
	ds_read_b128 v[140:143], v156 offset:704
	ds_read_b128 v[144:147], v154 offset:704
	ds_read_b128 v[148:151], v157 offset:704
	s_waitcnt vmcnt(5) lgkmcnt(6)
	v_mfma_f32_16x16x32_bf16 v[16:19], v[104:107], v[32:35], v[16:19]
	v_mfma_f32_16x16x32_bf16 v[12:15], v[112:115], v[32:35], v[12:15]
	v_mfma_f32_16x16x32_bf16 v[68:71], v[120:123], v[32:35], v[68:71]
	v_mfma_f32_16x16x32_bf16 v[16:19], v[108:111], v[32:35], v[16:19]
	v_mfma_f32_16x16x32_bf16 v[12:15], v[116:119], v[32:35], v[12:15]
	v_mfma_f32_16x16x32_bf16 v[68:71], v[124:127], v[32:35], v[68:71]
	ds_read_b128 v[104:107], v152 offset:768
	ds_read_b128 v[108:111], v155 offset:768
	ds_read_b128 v[112:115], v153 offset:768
	ds_read_b128 v[116:119], v156 offset:768
	ds_read_b128 v[120:123], v154 offset:768
	ds_read_b128 v[124:127], v157 offset:768
	s_waitcnt vmcnt(4) lgkmcnt(6)
	v_mfma_f32_16x16x32_bf16 v[16:19], v[128:131], v[28:31], v[16:19]
	v_mfma_f32_16x16x32_bf16 v[12:15], v[136:139], v[28:31], v[12:15]
	v_mfma_f32_16x16x32_bf16 v[68:71], v[144:147], v[28:31], v[68:71]
	v_mfma_f32_16x16x32_bf16 v[16:19], v[132:135], v[28:31], v[16:19]
	v_mfma_f32_16x16x32_bf16 v[12:15], v[140:143], v[28:31], v[12:15]
	v_mfma_f32_16x16x32_bf16 v[68:71], v[148:151], v[28:31], v[68:71]
	ds_read_b128 v[128:131], v152 offset:832
	ds_read_b128 v[132:135], v155 offset:832
	ds_read_b128 v[136:139], v153 offset:832
	ds_read_b128 v[140:143], v156 offset:832
	ds_read_b128 v[144:147], v154 offset:832
	ds_read_b128 v[148:151], v157 offset:832
	s_waitcnt vmcnt(3) lgkmcnt(6)
	v_mfma_f32_16x16x32_bf16 v[16:19], v[104:107], v[24:27], v[16:19]
	v_mfma_f32_16x16x32_bf16 v[12:15], v[112:115], v[24:27], v[12:15]
	v_mfma_f32_16x16x32_bf16 v[68:71], v[120:123], v[24:27], v[68:71]
	v_mfma_f32_16x16x32_bf16 v[16:19], v[108:111], v[24:27], v[16:19]
	v_mfma_f32_16x16x32_bf16 v[12:15], v[116:119], v[24:27], v[12:15]
	v_mfma_f32_16x16x32_bf16 v[68:71], v[124:127], v[24:27], v[68:71]
	ds_read_b128 v[104:107], v152 offset:896
	ds_read_b128 v[108:111], v155 offset:896
	ds_read_b128 v[112:115], v153 offset:896
	ds_read_b128 v[116:119], v156 offset:896
	ds_read_b128 v[120:123], v154 offset:896
	ds_read_b128 v[124:127], v157 offset:896
	s_waitcnt vmcnt(2) lgkmcnt(6)
	v_mfma_f32_16x16x32_bf16 v[16:19], v[128:131], v[20:23], v[16:19]
	v_mfma_f32_16x16x32_bf16 v[12:15], v[136:139], v[20:23], v[12:15]
	v_mfma_f32_16x16x32_bf16 v[68:71], v[144:147], v[20:23], v[68:71]
	v_mfma_f32_16x16x32_bf16 v[16:19], v[132:135], v[20:23], v[16:19]
	v_mfma_f32_16x16x32_bf16 v[12:15], v[140:143], v[20:23], v[12:15]
	v_mfma_f32_16x16x32_bf16 v[68:71], v[148:151], v[20:23], v[68:71]
	ds_read_b128 v[128:131], v152 offset:960
	ds_read_b128 v[132:135], v155 offset:960
	ds_read_b128 v[136:139], v153 offset:960
	ds_read_b128 v[140:143], v156 offset:960
	ds_read_b128 v[144:147], v154 offset:960
	ds_read_b128 v[148:151], v157 offset:960
	s_waitcnt vmcnt(1) lgkmcnt(6)
	v_mfma_f32_16x16x32_bf16 v[16:19], v[104:107], v[8:11], v[16:19]
	v_mfma_f32_16x16x32_bf16 v[12:15], v[112:115], v[8:11], v[12:15]
	v_mfma_f32_16x16x32_bf16 v[68:71], v[120:123], v[8:11], v[68:71]
	v_mfma_f32_16x16x32_bf16 v[16:19], v[108:111], v[8:11], v[16:19]
	v_mfma_f32_16x16x32_bf16 v[12:15], v[116:119], v[8:11], v[12:15]
	v_mfma_f32_16x16x32_bf16 v[68:71], v[124:127], v[8:11], v[68:71]
	s_waitcnt vmcnt(0) lgkmcnt(0)
	v_mfma_f32_16x16x32_bf16 v[16:19], v[128:131], v[4:7], v[16:19]
	v_mfma_f32_16x16x32_bf16 v[12:15], v[136:139], v[4:7], v[12:15]
	v_mfma_f32_16x16x32_bf16 v[68:71], v[144:147], v[4:7], v[68:71]
	v_mfma_f32_16x16x32_bf16 v[16:19], v[132:135], v[4:7], v[16:19]
	v_mfma_f32_16x16x32_bf16 v[12:15], v[140:143], v[4:7], v[12:15]
	v_mfma_f32_16x16x32_bf16 v[68:71], v[148:151], v[4:7], v[68:71]
	s_mov_b64 s[6:7], 0
	s_cbranch_vccz .LBB0_1171
	v_cmp_gt_i32_e32 vcc, s28, v86
	s_and_saveexec_b64 s[6:7], vcc
	s_cbranch_execz .LBB0_1169
	s_movk_i32 s8, 0xc0
	v_mad_i64_i32 v[4:5], s[12:13], v78, s8, v[76:77]
	global_store_dwordx4 v[4:5], v[16:19], off
	global_store_dwordx4 v[4:5], v[12:15], off offset:64
	global_store_dwordx4 v[4:5], v[68:71], off offset:128
	s_branch .LBB0_1169
